# aligned rotated mixer-A loop plus out-of-line last-tile path (no taken branch inside the tile body)
# speedup vs baseline: 1.0101x; 1.0043x over previous
.LBB0_407:
	v_mbcnt_lo_u32_b32 v128, -1, 0
	v_mbcnt_hi_u32_b32 v128, -1, v128
	s_add_i32 s7, s7, 0
	v_bfe_u32 v129, v128, 2, 2
	v_lshrrev_b32_e32 v130, 3, v128
	v_bfe_u32 v132, v128, 1, 1
	v_and_or_b32 v131, v130, s64, v129
	v_and_or_b32 v130, v130, 2, v132
	v_lshlrev_b32_e32 v128, 3, v128
	v_lshlrev_b32_e32 v131, 8, v131
	v_lshlrev_b32_e32 v130, 4, v130
	v_and_b32_e32 v128, 8, v128
	v_or3_b32 v160, v130, v131, v128
	v_lshlrev_b32_e32 v162, 6, v129
	v_mbcnt_lo_u32_b32 v128, -1, 0
	v_mbcnt_hi_u32_b32 v128, -1, v128
	v_or_b32_e32 v163, v160, v162
	v_ashrrev_i32_e32 v129, 5, v128
	v_lshlrev_b32_e32 v130, 7, v128
	v_lshrrev_b32_e32 v133, 1, v128
	v_and_b32_e32 v132, 0xf80, v130
	v_bitop3_b32 v128, v133, v129, 7 bitop3:0x6c
	v_lshl_add_u32 v134, v128, 4, v132
	v_add_u32_e32 v128, 2, v129
	v_bitop3_b32 v128, v128, v133, 7 bitop3:0x78
	v_lshl_add_u32 v136, v128, 4, v132
	v_add_u32_e32 v128, 4, v129
	v_bitop3_b32 v128, v128, v133, 7 bitop3:0x78
	v_add_u32_e32 v207, s7, v134
	v_lshl_add_u32 v168, v128, 4, v132
	v_add_u32_e32 v135, 6, v129
	ds_read_b128 v[128:131], v207
	v_bitop3_b32 v133, v135, v133, 7 bitop3:0x78
	v_add_u32_e32 v224, s48, v134
	v_add_u32_e32 v225, s7, v136
	v_lshl_add_u32 v169, v133, 4, v132
	ds_read_b128 v[132:135], v224
	v_add_u32_e32 v226, s48, v136
	ds_read_b128 v[136:139], v225
	ds_read_b128 v[140:143], v226
	v_bitop3_b32 v203, v160, s37, v162 bitop3:0x36
	v_bitop3_b32 v206, v160, s41, v162 bitop3:0x36
	s_waitcnt lgkmcnt(2)
	v_mfma_f32_32x32x16_bf16 v[144:159], v[128:131], v[132:135], 0
	v_add_u32_e32 v227, s7, v168
	v_add_u32_e32 v228, s48, v168
	ds_read_b128 v[128:131], v227
	ds_read_b128 v[132:135], v228
	s_waitcnt lgkmcnt(2)
	v_mfma_f32_32x32x16_bf16 v[144:159], v[136:139], v[140:143], v[144:159]
	v_add_u32_e32 v230, s7, v169
	v_add_u32_e32 v232, s48, v169
	ds_read_b128 v[136:139], v230
	ds_read_b128 v[140:143], v232
	s_waitcnt lgkmcnt(2)
	v_mfma_f32_32x32x16_bf16 v[144:159], v[128:131], v[132:135], v[144:159]
	ds_read_b128 v[128:131], v207 offset:8192
	ds_read_b128 v[132:135], v224 offset:4096
	s_waitcnt lgkmcnt(2)
	v_mfma_f32_32x32x16_bf16 v[144:159], v[136:139], v[140:143], v[144:159]
	ds_read_b128 v[178:181], v225 offset:8192
	ds_read_b128 v[182:185], v226 offset:4096
	s_waitcnt lgkmcnt(2)
	v_mfma_f32_32x32x16_bf16 v[128:143], v[128:131], v[132:135], 0
	s_nop 7
	v_exp_f32_e32 v173, v144
	v_exp_f32_e32 v169, v145
	v_exp_f32_e32 v177, v146
	v_exp_f32_e32 v171, v147
	ds_read_b128 v[144:147], v227 offset:8192
	ds_read_b128 v[190:193], v228 offset:4096
	s_waitcnt lgkmcnt(2)
	v_mfma_f32_32x32x16_bf16 v[128:143], v[178:181], v[182:185], v[128:143]
	v_exp_f32_e32 v183, v148
	v_exp_f32_e32 v175, v149
	v_exp_f32_e32 v189, v150
	v_exp_f32_e32 v179, v151
	ds_read_b128 v[148:151], v230 offset:8192
	ds_read_b128 v[196:199], v232 offset:4096
	s_waitcnt lgkmcnt(2)
	v_mfma_f32_32x32x16_bf16 v[128:143], v[144:147], v[190:193], v[128:143]
	v_exp_f32_e32 v193, v152
	v_exp_f32_e32 v181, v153
	v_exp_f32_e32 v195, v154
	v_exp_f32_e32 v187, v155
	s_waitcnt lgkmcnt(0)
	v_mfma_f32_32x32x16_bf16 v[128:143], v[148:151], v[196:199], v[128:143]
	v_exp_f32_e32 v197, v156
	v_exp_f32_e32 v185, v157
	v_exp_f32_e32 v199, v158
	v_exp_f32_e32 v191, v159
	s_cmp_eq_u32 s4, 0x3f0000
	s_cbranch_scc1 .Lattn_nodma_a
	v_mov_b32_e32 v213, 0
	v_add_u32_e32 v212, s4, v202
	s_xor_b32 s8, s7, 0x4000
	v_lshl_add_u64 v[208:209], v[212:213], 1, s[66:67]
	s_add_i32 s9, s49, s8
	s_mov_b32 s10, m0
	s_mov_b32 m0, s9
	s_nop 0
	global_load_lds_dwordx4 v[208:209], off
	s_mov_b32 m0, s10
	v_add_u32_e32 v210, s4, v201
	v_lshl_add_u64 v[208:209], v[208:209], 0, s[38:39]
	s_add_i32 s9, s33, s8
	s_mov_b32 s10, m0
	s_mov_b32 m0, s9
	s_nop 0
	global_load_lds_dwordx4 v[208:209], off
	s_mov_b32 m0, s10
	v_add_u32_e32 v212, 0x10000, v210
	v_lshl_add_u64 v[208:209], v[212:213], 1, s[68:69]
	s_add_i32 s9, s54, s8
	s_mov_b32 s10, m0
	s_mov_b32 m0, s9
	s_nop 0
	global_load_lds_dwordx4 v[208:209], off
	s_mov_b32 m0, s10
	v_add_u32_e32 v212, 0x18000, v210
	v_lshl_add_u64 v[208:209], v[212:213], 1, s[68:69]
	s_add_i32 s8, s47, s8
	s_mov_b32 s9, m0
	s_mov_b32 m0, s8
	s_nop 0
	global_load_lds_dwordx4 v[208:209], off
	s_mov_b32 m0, s9
.Lattn_dma_done_a:
	v_exp_f32_e32 v172, v128
	v_exp_f32_e32 v170, v129
	v_exp_f32_e32 v176, v130
	v_exp_f32_e32 v168, v131
	v_exp_f32_e32 v182, v132
	v_exp_f32_e32 v178, v133
	v_exp_f32_e32 v188, v134
	v_exp_f32_e32 v174, v135
	v_exp_f32_e32 v192, v136
	v_exp_f32_e32 v186, v137
	v_exp_f32_e32 v194, v138
	v_exp_f32_e32 v180, v139
	v_exp_f32_e32 v196, v140
	v_exp_f32_e32 v190, v141
	v_exp_f32_e32 v198, v142
	v_exp_f32_e32 v184, v143
	v_cvt_pk_bf16_f32 v144, v173, v169
	v_cvt_pk_bf16_f32 v145, v177, v171
	v_cvt_pk_bf16_f32 v146, v183, v175
	v_cvt_pk_bf16_f32 v147, v189, v179
	v_cvt_pk_bf16_f32 v148, v193, v181
	v_cvt_pk_bf16_f32 v149, v195, v187
	v_cvt_pk_bf16_f32 v150, v197, v185
	v_cvt_pk_bf16_f32 v151, v199, v191
	v_cvt_pk_bf16_f32 v128, v172, v170
	v_cvt_pk_bf16_f32 v129, v176, v168
	v_cvt_pk_bf16_f32 v130, v182, v178
	v_cvt_pk_bf16_f32 v131, v188, v174
	v_cvt_pk_bf16_f32 v132, v192, v186
	v_cvt_pk_bf16_f32 v133, v194, v180
	v_cvt_pk_bf16_f32 v134, v196, v190
	v_cvt_pk_bf16_f32 v135, v198, v184
	v_add3_u32 v160, s7, v162, v160
	v_xad_u32 v252, v163, 64, s7
	v_add_u32_e32 v203, s7, v203
	v_add_u32_e32 v205, s7, v206
	ds_read_b64_tr_b16 v[136:137], v160 offset:32768
	ds_read_b64_tr_b16 v[138:139], v160 offset:34816
	ds_read_b64_tr_b16 v[140:141], v160 offset:36864
	ds_read_b64_tr_b16 v[142:143], v160 offset:38912
	ds_read_b64_tr_b16 v[152:153], v252 offset:32768
	ds_read_b64_tr_b16 v[154:155], v252 offset:34816
	ds_read_b64_tr_b16 v[156:157], v252 offset:36864
	ds_read_b64_tr_b16 v[158:159], v252 offset:38912
	ds_read_b64_tr_b16 v[208:209], v203 offset:32768
	ds_read_b64_tr_b16 v[210:211], v203 offset:34816
	ds_read_b64_tr_b16 v[212:213], v203 offset:36864
	ds_read_b64_tr_b16 v[214:215], v203 offset:38912
	ds_read_b64_tr_b16 v[216:217], v205 offset:32768
	ds_read_b64_tr_b16 v[218:219], v205 offset:34816
	ds_read_b64_tr_b16 v[220:221], v205 offset:36864
	ds_read_b64_tr_b16 v[222:223], v205 offset:38912
	s_waitcnt lgkmcnt(14)
	v_mfma_f32_32x32x16_bf16 v[64:79], v[144:147], v[136:139], v[64:79]
	v_mfma_f32_32x32x16_bf16 v[0:15], v[128:131], v[136:139], v[0:15]
	s_waitcnt lgkmcnt(10)
	v_mfma_f32_32x32x16_bf16 v[80:95], v[144:147], v[152:155], v[80:95]
	v_mfma_f32_32x32x16_bf16 v[16:31], v[128:131], v[152:155], v[16:31]
	s_waitcnt lgkmcnt(6)
	v_mfma_f32_32x32x16_bf16 v[96:111], v[144:147], v[208:211], v[96:111]
	v_mfma_f32_32x32x16_bf16 v[32:47], v[128:131], v[208:211], v[32:47]
	s_waitcnt lgkmcnt(2)
	v_mfma_f32_32x32x16_bf16 v[112:127], v[144:147], v[216:219], v[112:127]
	v_mfma_f32_32x32x16_bf16 v[48:63], v[128:131], v[216:219], v[48:63]
	v_mfma_f32_32x32x16_bf16 v[64:79], v[148:151], v[140:143], v[64:79]
	v_mfma_f32_32x32x16_bf16 v[0:15], v[132:135], v[140:143], v[0:15]
	v_mfma_f32_32x32x16_bf16 v[80:95], v[148:151], v[156:159], v[80:95]
	v_mfma_f32_32x32x16_bf16 v[16:31], v[132:135], v[156:159], v[16:31]
	v_mfma_f32_32x32x16_bf16 v[96:111], v[148:151], v[212:215], v[96:111]
	v_mfma_f32_32x32x16_bf16 v[32:47], v[132:135], v[212:215], v[32:47]
	s_waitcnt lgkmcnt(0)
	v_mfma_f32_32x32x16_bf16 v[112:127], v[148:151], v[220:223], v[112:127]
	v_mfma_f32_32x32x16_bf16 v[48:63], v[132:135], v[220:223], v[48:63]
	ds_read_b128 v[128:131], v207 offset:4096
	ds_read_b128 v[132:135], v224
	ds_read_b128 v[136:139], v225 offset:4096
	ds_read_b128 v[140:143], v226
	s_waitcnt lgkmcnt(2)
	v_mfma_f32_32x32x16_bf16 v[144:159], v[128:131], v[132:135], 0
	ds_read_b128 v[128:131], v227 offset:4096
	ds_read_b128 v[132:135], v228
	s_waitcnt lgkmcnt(2)
	v_mfma_f32_32x32x16_bf16 v[144:159], v[136:139], v[140:143], v[144:159]
	ds_read_b128 v[136:139], v230 offset:4096
	ds_read_b128 v[140:143], v232
	s_waitcnt lgkmcnt(2)
	v_mfma_f32_32x32x16_bf16 v[144:159], v[128:131], v[132:135], v[144:159]
	ds_read_b128 v[128:131], v207 offset:12288
	ds_read_b128 v[132:135], v224 offset:4096
	s_waitcnt lgkmcnt(2)
	v_mfma_f32_32x32x16_bf16 v[144:159], v[136:139], v[140:143], v[144:159]
	ds_read_b128 v[208:211], v225 offset:12288
	ds_read_b128 v[212:215], v226 offset:4096
	s_waitcnt lgkmcnt(2)
	v_mfma_f32_32x32x16_bf16 v[128:143], v[128:131], v[132:135], 0
	s_nop 7
	v_exp_f32_e32 v229, v144
	v_exp_f32_e32 v145, v145
	v_exp_f32_e32 v231, v146
	v_exp_f32_e32 v147, v147
	ds_read_b128 v[216:219], v227 offset:12288
	ds_read_b128 v[220:223], v228 offset:4096
	s_waitcnt lgkmcnt(2)
	v_mfma_f32_32x32x16_bf16 v[128:143], v[208:211], v[212:215], v[128:143]
	v_exp_f32_e32 v233, v148
	v_exp_f32_e32 v235, v149
	v_exp_f32_e32 v237, v150
	v_exp_f32_e32 v239, v151
	ds_read_b128 v[148:151], v230 offset:12288
	ds_read_b128 v[208:211], v232 offset:4096
	s_waitcnt lgkmcnt(2)
	v_mfma_f32_32x32x16_bf16 v[128:143], v[216:219], v[220:223], v[128:143]
	v_exp_f32_e32 v241, v152
	v_exp_f32_e32 v243, v153
	v_exp_f32_e32 v245, v154
	v_exp_f32_e32 v247, v155
	s_waitcnt lgkmcnt(0)
	v_mfma_f32_32x32x16_bf16 v[128:143], v[148:151], v[208:211], v[128:143]
	v_exp_f32_e32 v249, v156
	v_exp_f32_e32 v251, v157
	v_exp_f32_e32 v207, v158
	v_exp_f32_e32 v163, v159
	s_nop 7
	v_exp_f32_e32 v228, v128
	v_exp_f32_e32 v146, v129
	v_exp_f32_e32 v230, v130
	v_exp_f32_e32 v144, v131
	v_exp_f32_e32 v232, v132
	v_exp_f32_e32 v238, v133
	v_exp_f32_e32 v236, v134
	v_exp_f32_e32 v234, v135
	v_exp_f32_e32 v240, v136
	v_exp_f32_e32 v246, v137
	v_exp_f32_e32 v244, v138
	v_exp_f32_e32 v242, v139
	v_exp_f32_e32 v248, v140
	v_exp_f32_e32 v162, v141
	v_exp_f32_e32 v206, v142
	v_exp_f32_e32 v250, v143
	v_cvt_pk_bf16_f32 v148, v229, v145
	v_cvt_pk_bf16_f32 v149, v231, v147
	v_cvt_pk_bf16_f32 v150, v233, v235
	v_cvt_pk_bf16_f32 v151, v237, v239
	v_cvt_pk_bf16_f32 v152, v241, v243
	v_cvt_pk_bf16_f32 v153, v245, v247
	v_cvt_pk_bf16_f32 v154, v249, v251
	v_cvt_pk_bf16_f32 v155, v207, v163
	v_cvt_pk_bf16_f32 v128, v228, v146
	v_cvt_pk_bf16_f32 v129, v230, v144
	v_cvt_pk_bf16_f32 v130, v232, v238
	v_cvt_pk_bf16_f32 v131, v236, v234
	v_cvt_pk_bf16_f32 v132, v240, v246
	v_cvt_pk_bf16_f32 v133, v244, v242
	v_cvt_pk_bf16_f32 v134, v248, v162
	v_cvt_pk_bf16_f32 v135, v206, v250
	ds_read_b64_tr_b16 v[136:137], v160 offset:40960
	ds_read_b64_tr_b16 v[138:139], v160 offset:43008
	ds_read_b64_tr_b16 v[140:141], v160 offset:45056
	ds_read_b64_tr_b16 v[142:143], v160 offset:47104
	ds_read_b64_tr_b16 v[156:157], v252 offset:40960
	ds_read_b64_tr_b16 v[158:159], v252 offset:43008
	ds_read_b64_tr_b16 v[208:209], v252 offset:45056
	ds_read_b64_tr_b16 v[210:211], v252 offset:47104
	ds_read_b64_tr_b16 v[212:213], v203 offset:40960
	ds_read_b64_tr_b16 v[214:215], v203 offset:43008
	ds_read_b64_tr_b16 v[216:217], v203 offset:45056
	ds_read_b64_tr_b16 v[218:219], v203 offset:47104
	ds_read_b64_tr_b16 v[220:221], v205 offset:40960
	ds_read_b64_tr_b16 v[222:223], v205 offset:43008
	ds_read_b64_tr_b16 v[224:225], v205 offset:45056
	ds_read_b64_tr_b16 v[226:227], v205 offset:47104
	s_waitcnt lgkmcnt(14)
	v_mfma_f32_32x32x16_bf16 v[64:79], v[148:151], v[136:139], v[64:79]
	v_mfma_f32_32x32x16_bf16 v[0:15], v[128:131], v[136:139], v[0:15]
	s_waitcnt lgkmcnt(10)
	v_mfma_f32_32x32x16_bf16 v[80:95], v[148:151], v[156:159], v[80:95]
	v_mfma_f32_32x32x16_bf16 v[16:31], v[128:131], v[156:159], v[16:31]
	s_waitcnt lgkmcnt(6)
	v_mfma_f32_32x32x16_bf16 v[96:111], v[148:151], v[212:215], v[96:111]
	v_mfma_f32_32x32x16_bf16 v[32:47], v[128:131], v[212:215], v[32:47]
	s_waitcnt lgkmcnt(2)
	v_mfma_f32_32x32x16_bf16 v[112:127], v[148:151], v[220:223], v[112:127]
	v_mfma_f32_32x32x16_bf16 v[48:63], v[128:131], v[220:223], v[48:63]
	v_add_f32_e64 v128, v172, v176
	v_add_f32_e64 v129, v173, v177
	v_add_f32_e64 v130, v168, v170
	v_add_f32_e64 v131, v169, v171
	v_add_f32_e64 v128, v128, 0
	v_add_f32_e64 v129, v129, 0
	v_pk_add_f32 v[136:137], v[182:183], v[188:189]
	v_pk_add_f32 v[130:131], v[130:131], 0 op_sel_hi:[1,0]
	v_pk_add_f32 v[128:129], v[136:137], v[128:129]
	v_pk_add_f32 v[136:137], v[174:175], v[178:179]
	v_pk_add_f32 v[138:139], v[232:233], v[236:237]
	v_pk_add_f32 v[130:131], v[136:137], v[130:131]
	v_pk_add_f32 v[136:137], v[192:193], v[194:195]
	v_mfma_f32_32x32x16_bf16 v[64:79], v[152:155], v[140:143], v[64:79]
	v_add_f32_e64 v128, v136, v128
	v_add_f32_e64 v129, v137, v129
	v_add_f32_e64 v136, v180, v186
	v_add_f32_e64 v137, v181, v187
	v_add_f32_e64 v130, v136, v130
	v_add_f32_e64 v131, v137, v131
	v_pk_add_f32 v[136:137], v[196:197], v[198:199]
	s_nop 0
	v_pk_add_f32 v[128:129], v[136:137], v[128:129]
	v_pk_add_f32 v[136:137], v[184:185], v[190:191]
	v_mfma_f32_32x32x16_bf16 v[0:15], v[132:135], v[140:143], v[0:15]
	v_add_f32_e64 v130, v136, v130
	v_add_f32_e64 v131, v137, v131
	v_add_f32_e64 v136, v144, v146
	v_add_f32_e64 v137, v145, v147
	v_add_f32_e64 v128, v128, v130
	v_add_f32_e64 v129, v129, v131
	v_pk_add_f32 v[130:131], v[228:229], v[230:231]
	v_pk_add_f32 v[136:137], v[136:137], 0 op_sel_hi:[1,0]
	v_pk_add_f32 v[130:131], v[130:131], 0 op_sel_hi:[1,0]
	v_pk_add_f32 v[128:129], v[166:167], v[128:129]
	v_mfma_f32_32x32x16_bf16 v[80:95], v[152:155], v[208:211], v[80:95]
	v_add_f32_e64 v130, v138, v130
	v_add_f32_e64 v131, v139, v131
	v_add_f32_e64 v138, v234, v238
	v_add_f32_e64 v139, v235, v239
	v_add_f32_e64 v136, v138, v136
	v_add_f32_e64 v137, v139, v137
	v_pk_add_f32 v[138:139], v[240:241], v[244:245]
	s_nop 0
	v_pk_add_f32 v[130:131], v[138:139], v[130:131]
	v_mfma_f32_32x32x16_bf16 v[16:31], v[132:135], v[208:211], v[16:31]
	v_add_f32_e64 v138, v242, v246
	v_add_f32_e64 v139, v243, v247
	v_add_f32_e64 v136, v138, v136
	v_add_f32_e64 v137, v139, v137
	v_add_f32_e64 v138, v248, v206
	v_add_f32_e64 v139, v249, v207
	v_pk_add_f32 v[130:131], v[138:139], v[130:131]
	v_pk_add_f32 v[138:139], v[250:251], v[162:163]
	v_mfma_f32_32x32x16_bf16 v[96:111], v[152:155], v[216:219], v[96:111]
	v_add_f32_e64 v136, v138, v136
	v_add_f32_e64 v137, v139, v137
	v_add_f32_e64 v130, v130, v136
	v_add_f32_e64 v131, v131, v137
	v_add_f32_e64 v166, v128, v130
	v_add_f32_e64 v167, v129, v131
	v_mfma_f32_32x32x16_bf16 v[32:47], v[132:135], v[216:219], v[32:47]
	s_waitcnt lgkmcnt(0)
	v_mfma_f32_32x32x16_bf16 v[112:127], v[152:155], v[224:227], v[112:127]
	v_mfma_f32_32x32x16_bf16 v[48:63], v[132:135], v[224:227], v[48:63]
	s_waitcnt vmcnt(0)
	s_waitcnt lgkmcnt(0)
	s_addk_i32 s5, 0x4000
	s_add_i32 s4, s4, 0x10000
	s_and_b32 s7, s5, 0x4000
	s_cmp_eq_u32 s4, 0x400000
	s_cbranch_scc0 .Lattn_head_a
	s_barrier
